# gate-up epilogue: the 64 load-independent gate*up multiplies moved above the row-statistics wait (wait at first consumer); on top of v23
# baseline (speedup 1.0000x reference)
; __device__ __forceinline__ float sigm(float x) { return __builtin_amdgcn_rcpf(1.0f + __expf(-x)); }
; __device__ __forceinline__ u32x4 pack8(f32x4 a, f32x4 b) { u32x4 w; w.x = cvt_pk_bf16(a[0], a[1]); w.y = cvt_pk_bf16(a[2], a[3]); w.z = cvt_pk_bf16(b[0], b[1]); w.w = cvt_pk_bf16(b[2], b[3]); return w; }
; __device__ __forceinline__ void rstd8(const float* SS, int row0, int fq, float (&r)[2][4]) {
;     f32x4 v[2][4];
; #pragma unroll
;     for (int ai = 0; ai < 2; ++ai)
; #pragma unroll
;         for (int m = 0; m < 4; ++m) v[ai][m] = *(const f32x4*)(SS + (size_t)(row0 + ai * 128 + m * 16) * 16 + 4 * fq);
; #pragma unroll
;     for (int ai = 0; ai < 2; ++ai)
; #pragma unroll
;         for (int m = 0; m < 4; ++m) { float s = (v[ai][m][0] + v[ai][m][1]) + (v[ai][m][2] + v[ai][m][3]); s += __shfl_xor(s, 16); s += __shfl_xor(s, 32); r[ai][m] = rsqrtf(s * (1.0f / 1024.0f) + 1e-6f); }
; }
;     __device__ __forceinline__ void operator()(const f32x4 (&acc)[2][2][4][2], const Unit& u, int wr, int wc, int fr_, int fq_) const {
;         int fr = fr_, fq = fq_; asm volatile("" : "+v"(fr), "+v"(fq));
;         float rs8[2][4]; rstd8(SS, u.pm * 256 + wr * 64 + fr, fq, rs8);
; #pragma unroll
;         for (int ai = 0; ai < 2; ++ai)
; #pragma unroll
;             for (int m = 0; m < 4; ++m) {
;                 const int row = u.pm * 256 + ai * 128 + wr * 64 + m * 16 + fr;
;                 const float rstd = rs8[ai][m];
;                 f32x4 o[2];
; #pragma unroll
;                 for (int n = 0; n < 2; ++n) { const f32x4 g = acc[ai][0][m][n] * rstd, up = acc[ai][1][m][n] * rstd;
; #pragma unroll
;                     for (int i = 0; i < 4; ++i) o[n][i] = g[i] * sigm(g[i]) * up[i]; }
;                 *(u32x4*)(ACT + (size_t)row * DFF + 128 * u.pn + 32 * wc + 8 * fq) = pack8(o[0], o[1]);
.LBB0_50:
	s_lshl_b32 s0, s0, 8
	s_add_i32 s0, s0, s68
	v_add_u32_e32 v168, s0, v184
	v_lshlrev_b32_e32 v169, 4, v185
	v_lshl_add_u32 v169, v168, 6, v169
	global_load_dwordx4 v[130:133], v169, s[46:47]
	global_load_dwordx4 v[134:137], v169, s[46:47] offset:1024
	global_load_dwordx4 v[138:141], v169, s[46:47] offset:2048
	global_load_dwordx4 v[142:145], v169, s[46:47] offset:3072
	v_add_u32_e32 v169, 0x2000, v169
	global_load_dwordx4 v[146:149], v169, s[46:47]
	global_load_dwordx4 v[150:153], v169, s[46:47] offset:1024
	global_load_dwordx4 v[154:157], v169, s[46:47] offset:2048
	global_load_dwordx4 v[158:161], v169, s[46:47] offset:3072
	v_xor_b32_e32 v170, 16, v203
	v_xor_b32_e32 v171, 32, v203
	v_lshlrev_b32_e32 v170, 2, v170
	v_lshlrev_b32_e32 v171, 2, v171
	s_movk_i32 s21, 0x1600
	v_readlane_b32 s30, v253, 13
	v_readlane_b32 s31, v253, 14
	s_lshl_b32 s0, s44, 8
	s_add_i32 s0, s0, s24
	v_mul_lo_u32 v172, v168, s21
	v_lshl_add_u32 v173, v185, 4, s0
	v_add_u32_e32 v172, v172, v173
	s_mov_b32 s0, 0x3a800000
	v_mov_b32_e32 v173, 0x358637bd
	v_mul_f32_e32 v126, v122, v126
	v_mul_f32_e32 v127, v123, v127
	v_mul_f32_e32 v128, v124, v128
	v_mul_f32_e32 v129, v125, v129
	v_mul_f32_e32 v118, v114, v118
	v_mul_f32_e32 v119, v115, v119
	v_mul_f32_e32 v120, v116, v120
	v_mul_f32_e32 v121, v117, v121
	v_mul_f32_e32 v110, v106, v110
	v_mul_f32_e32 v111, v107, v111
	v_mul_f32_e32 v112, v108, v112
	v_mul_f32_e32 v113, v109, v113
	v_mul_f32_e32 v102, v98, v102
	v_mul_f32_e32 v103, v99, v103
	v_mul_f32_e32 v104, v100, v104
	v_mul_f32_e32 v105, v101, v105
	v_mul_f32_e32 v94, v90, v94
	v_mul_f32_e32 v95, v91, v95
	v_mul_f32_e32 v96, v92, v96
	v_mul_f32_e32 v97, v93, v97
	v_mul_f32_e32 v86, v82, v86
	v_mul_f32_e32 v87, v83, v87
	v_mul_f32_e32 v88, v84, v88
	v_mul_f32_e32 v89, v85, v89
	v_mul_f32_e32 v78, v74, v78
	v_mul_f32_e32 v79, v75, v79
	v_mul_f32_e32 v80, v76, v80
	v_mul_f32_e32 v81, v77, v81
	v_mul_f32_e32 v70, v66, v70
	v_mul_f32_e32 v71, v67, v71
	v_mul_f32_e32 v72, v68, v72
	v_mul_f32_e32 v73, v69, v73
	v_mul_f32_e32 v62, v58, v62
	v_mul_f32_e32 v63, v59, v63
	v_mul_f32_e32 v64, v60, v64
	v_mul_f32_e32 v65, v61, v65
	v_mul_f32_e32 v54, v50, v54
	v_mul_f32_e32 v55, v51, v55
	v_mul_f32_e32 v56, v52, v56
	v_mul_f32_e32 v57, v53, v57
	v_mul_f32_e32 v46, v42, v46
	v_mul_f32_e32 v47, v43, v47
	v_mul_f32_e32 v48, v44, v48
	v_mul_f32_e32 v49, v45, v49
	v_mul_f32_e32 v38, v34, v38
	v_mul_f32_e32 v39, v35, v39
	v_mul_f32_e32 v40, v36, v40
	v_mul_f32_e32 v41, v37, v41
	v_mul_f32_e32 v30, v26, v30
	v_mul_f32_e32 v31, v27, v31
	v_mul_f32_e32 v32, v28, v32
	v_mul_f32_e32 v33, v29, v33
	v_mul_f32_e32 v22, v18, v22
	v_mul_f32_e32 v23, v19, v23
	v_mul_f32_e32 v24, v20, v24
	v_mul_f32_e32 v25, v21, v25
	v_mul_f32_e32 v14, v10, v14
	v_mul_f32_e32 v15, v11, v15
	v_mul_f32_e32 v16, v12, v16
	v_mul_f32_e32 v17, v13, v17
	v_mul_f32_e32 v6, v2, v6
	v_mul_f32_e32 v7, v3, v7
	v_mul_f32_e32 v8, v4, v8
	v_mul_f32_e32 v9, v5, v9
	s_waitcnt vmcnt(0)
	v_add_f32_e32 v130, v130, v131
	v_add_f32_e32 v132, v132, v133
	v_add_f32_e32 v134, v134, v135
	v_add_f32_e32 v136, v136, v137
	v_add_f32_e32 v138, v138, v139
	v_add_f32_e32 v140, v140, v141
	v_add_f32_e32 v142, v142, v143
	v_add_f32_e32 v144, v144, v145
	v_add_f32_e32 v146, v146, v147
	v_add_f32_e32 v148, v148, v149
	v_add_f32_e32 v150, v150, v151
	v_add_f32_e32 v152, v152, v153
	v_add_f32_e32 v154, v154, v155
	v_add_f32_e32 v156, v156, v157
	v_add_f32_e32 v158, v158, v159
	v_add_f32_e32 v160, v160, v161
	v_add_f32_e32 v130, v130, v132
	v_add_f32_e32 v134, v134, v136
	v_add_f32_e32 v138, v138, v140
	v_add_f32_e32 v142, v142, v144
	v_add_f32_e32 v146, v146, v148
	v_add_f32_e32 v150, v150, v152
	v_add_f32_e32 v154, v154, v156
	v_add_f32_e32 v158, v158, v160
	ds_bpermute_b32 v131, v170, v130
	ds_bpermute_b32 v135, v170, v134
	ds_bpermute_b32 v139, v170, v138
	ds_bpermute_b32 v143, v170, v142
	ds_bpermute_b32 v147, v170, v146
	ds_bpermute_b32 v151, v170, v150
	ds_bpermute_b32 v155, v170, v154
	ds_bpermute_b32 v159, v170, v158
	s_waitcnt lgkmcnt(0)
	v_add_f32_e32 v130, v130, v131
	v_add_f32_e32 v134, v134, v135
	v_add_f32_e32 v138, v138, v139
	v_add_f32_e32 v142, v142, v143
	v_add_f32_e32 v146, v146, v147
	v_add_f32_e32 v150, v150, v151
	v_add_f32_e32 v154, v154, v155
	v_add_f32_e32 v158, v158, v159
	ds_bpermute_b32 v131, v171, v130
	ds_bpermute_b32 v135, v171, v134
	ds_bpermute_b32 v139, v171, v138
	ds_bpermute_b32 v143, v171, v142
	ds_bpermute_b32 v147, v171, v146
	ds_bpermute_b32 v151, v171, v150
	ds_bpermute_b32 v155, v171, v154
	ds_bpermute_b32 v159, v171, v158
	s_waitcnt lgkmcnt(0)
; __device__ __forceinline__ float sigm(float x) { return __builtin_amdgcn_rcpf(1.0f + __expf(-x)); }
; __device__ __forceinline__ u32x4 pack8(f32x4 a, f32x4 b) { u32x4 w; w.x = cvt_pk_bf16(a[0], a[1]); w.y = cvt_pk_bf16(a[2], a[3]); w.z = cvt_pk_bf16(b[0], b[1]); w.w = cvt_pk_bf16(b[2], b[3]); return w; }
; __device__ __forceinline__ void rstd8(const float* SS, int row0, int fq, float (&r)[2][4]) {
;     ...
; #pragma unroll
;         for (int m = 0; m < 4; ++m) { float s = (v[ai][m][0] + v[ai][m][1]) + (v[ai][m][2] + v[ai][m][3]); s += __shfl_xor(s, 16); s += __shfl_xor(s, 32); r[ai][m] = rsqrtf(s * (1.0f / 1024.0f) + 1e-6f); }
; }
;     __device__ __forceinline__ void operator()(const f32x4 (&acc)[2][2][4][2], const Unit& u, int wr, int wc, int fr_, int fq_) const {
;         int fr = fr_, fq = fq_; asm volatile("" : "+v"(fr), "+v"(fq));
;         float rs8[2][4]; rstd8(SS, u.pm * 256 + wr * 64 + fr, fq, rs8);
; #pragma unroll
;         for (int ai = 0; ai < 2; ++ai)
; #pragma unroll
;             for (int m = 0; m < 4; ++m) {
;                 const int row = u.pm * 256 + ai * 128 + wr * 64 + m * 16 + fr;
;                 const float rstd = rs8[ai][m];
;                 f32x4 o[2];
; #pragma unroll
;                 for (int n = 0; n < 2; ++n) { const f32x4 g = acc[ai][0][m][n] * rstd, up = acc[ai][1][m][n] * rstd;
; #pragma unroll
;                     for (int i = 0; i < 4; ++i) o[n][i] = g[i] * sigm(g[i]) * up[i]; }
;                 *(u32x4*)(ACT + (size_t)row * DFF + 128 * u.pn + 32 * wc + 8 * fq) = pack8(o[0], o[1]);
	v_add_f32_e32 v130, v130, v131
	v_add_f32_e32 v134, v134, v135
	v_add_f32_e32 v138, v138, v139
	v_add_f32_e32 v142, v142, v143
	v_add_f32_e32 v146, v146, v147
	v_add_f32_e32 v150, v150, v151
	v_add_f32_e32 v154, v154, v155
	v_add_f32_e32 v158, v158, v159
	v_fma_f32 v130, v130, s0, v173
	v_fma_f32 v134, v134, s0, v173
	v_fma_f32 v138, v138, s0, v173
	v_fma_f32 v142, v142, s0, v173
	v_fma_f32 v146, v146, s0, v173
	v_fma_f32 v150, v150, s0, v173
	v_fma_f32 v154, v154, s0, v173
	v_fma_f32 v158, v158, s0, v173
	v_rsq_f32_e32 v131, v130
	v_rsq_f32_e32 v135, v134
	v_rsq_f32_e32 v139, v138
	v_rsq_f32_e32 v143, v142
	v_rsq_f32_e32 v147, v146
	v_rsq_f32_e32 v151, v150
	v_rsq_f32_e32 v155, v154
	v_rsq_f32_e32 v159, v158
	v_mul_f32_e32 v131, 0xbfb8aa3b, v131
	v_mul_f32_e32 v135, 0xbfb8aa3b, v135
	v_mul_f32_e32 v139, 0xbfb8aa3b, v139
	v_mul_f32_e32 v143, 0xbfb8aa3b, v143
	v_mul_f32_e32 v147, 0xbfb8aa3b, v147
	v_mul_f32_e32 v151, 0xbfb8aa3b, v151
	v_mul_f32_e32 v155, 0xbfb8aa3b, v155
	v_mul_f32_e32 v159, 0xbfb8aa3b, v159
	v_mul_f32_e32 v122, v131, v122
	v_mul_f32_e32 v123, v131, v123
	v_mul_f32_e32 v124, v131, v124
	v_mul_f32_e32 v125, v131, v125
	v_mul_f32_e32 v114, v131, v114
	v_mul_f32_e32 v115, v131, v115
	v_mul_f32_e32 v116, v131, v116
	v_mul_f32_e32 v117, v131, v117
	v_exp_f32_e32 v122, v122
	v_exp_f32_e32 v123, v123
	v_exp_f32_e32 v124, v124
	v_exp_f32_e32 v125, v125
	v_exp_f32_e32 v114, v114
	v_exp_f32_e32 v115, v115
	v_exp_f32_e32 v116, v116
	v_exp_f32_e32 v117, v117
	v_fma_f32 v122, v122, v130, v130
	v_fma_f32 v123, v123, v130, v130
	v_fma_f32 v124, v124, v130, v130
	v_fma_f32 v125, v125, v130, v130
	v_fma_f32 v114, v114, v130, v130
	v_fma_f32 v115, v115, v130, v130
	v_fma_f32 v116, v116, v130, v130
	v_fma_f32 v117, v117, v130, v130
	v_rcp_f32_e32 v122, v122
	v_rcp_f32_e32 v123, v123
	v_rcp_f32_e32 v124, v124
	v_rcp_f32_e32 v125, v125
	v_rcp_f32_e32 v114, v114
	v_rcp_f32_e32 v115, v115
	v_rcp_f32_e32 v116, v116
	v_rcp_f32_e32 v117, v117
	v_mul_f32_e32 v126, v126, v122
	v_mul_f32_e32 v127, v127, v123
	v_mul_f32_e32 v128, v128, v124
	v_mul_f32_e32 v129, v129, v125
	v_mul_f32_e32 v118, v118, v114
	v_mul_f32_e32 v119, v119, v115
	v_mul_f32_e32 v120, v120, v116
	v_mul_f32_e32 v121, v121, v117
	v_cvt_pk_bf16_f32 v122, v126, v127
	v_cvt_pk_bf16_f32 v123, v128, v129
	v_cvt_pk_bf16_f32 v124, v118, v119
	v_cvt_pk_bf16_f32 v125, v120, v121
	global_store_dwordx4 v172, v[122:125], s[30:31]
	v_add_u32_e32 v172, 0x16000, v172
	v_mul_f32_e32 v106, v135, v106
	v_mul_f32_e32 v107, v135, v107
	v_mul_f32_e32 v108, v135, v108
	v_mul_f32_e32 v109, v135, v109
	v_mul_f32_e32 v98, v135, v98
	v_mul_f32_e32 v99, v135, v99
	v_mul_f32_e32 v100, v135, v100
	v_mul_f32_e32 v101, v135, v101
	v_exp_f32_e32 v106, v106
	v_exp_f32_e32 v107, v107
	v_exp_f32_e32 v108, v108
	v_exp_f32_e32 v109, v109
	v_exp_f32_e32 v98, v98
	v_exp_f32_e32 v99, v99
	v_exp_f32_e32 v100, v100
	v_exp_f32_e32 v101, v101
	v_fma_f32 v106, v106, v134, v134
	v_fma_f32 v107, v107, v134, v134
	v_fma_f32 v108, v108, v134, v134
	v_fma_f32 v109, v109, v134, v134
	v_fma_f32 v98, v98, v134, v134
	v_fma_f32 v99, v99, v134, v134
	v_fma_f32 v100, v100, v134, v134
	v_fma_f32 v101, v101, v134, v134
	v_rcp_f32_e32 v106, v106
	v_rcp_f32_e32 v107, v107
	v_rcp_f32_e32 v108, v108
	v_rcp_f32_e32 v109, v109
	v_rcp_f32_e32 v98, v98
	v_rcp_f32_e32 v99, v99
	v_rcp_f32_e32 v100, v100
	v_rcp_f32_e32 v101, v101
	v_mul_f32_e32 v110, v110, v106
	v_mul_f32_e32 v111, v111, v107
	v_mul_f32_e32 v112, v112, v108
	v_mul_f32_e32 v113, v113, v109
	v_mul_f32_e32 v102, v102, v98
	v_mul_f32_e32 v103, v103, v99
	v_mul_f32_e32 v104, v104, v100
	v_mul_f32_e32 v105, v105, v101
	v_cvt_pk_bf16_f32 v106, v110, v111
	v_cvt_pk_bf16_f32 v107, v112, v113
	v_cvt_pk_bf16_f32 v108, v102, v103
	v_cvt_pk_bf16_f32 v109, v104, v105
	global_store_dwordx4 v172, v[106:109], s[30:31]
	v_add_u32_e32 v172, 0x16000, v172
	v_mul_f32_e32 v90, v139, v90
	v_mul_f32_e32 v91, v139, v91
	v_mul_f32_e32 v92, v139, v92
	v_mul_f32_e32 v93, v139, v93
	v_mul_f32_e32 v82, v139, v82
	v_mul_f32_e32 v83, v139, v83
	v_mul_f32_e32 v84, v139, v84
	v_mul_f32_e32 v85, v139, v85
	v_exp_f32_e32 v90, v90
	v_exp_f32_e32 v91, v91
	v_exp_f32_e32 v92, v92
	v_exp_f32_e32 v93, v93
	v_exp_f32_e32 v82, v82
	v_exp_f32_e32 v83, v83
	v_exp_f32_e32 v84, v84
	v_exp_f32_e32 v85, v85
	v_fma_f32 v90, v90, v138, v138
	v_fma_f32 v91, v91, v138, v138
	v_fma_f32 v92, v92, v138, v138
	v_fma_f32 v93, v93, v138, v138
	v_fma_f32 v82, v82, v138, v138
	v_fma_f32 v83, v83, v138, v138
	v_fma_f32 v84, v84, v138, v138
	v_fma_f32 v85, v85, v138, v138
	v_rcp_f32_e32 v90, v90
	v_rcp_f32_e32 v91, v91
	v_rcp_f32_e32 v92, v92
	v_rcp_f32_e32 v93, v93
	v_rcp_f32_e32 v82, v82
	v_rcp_f32_e32 v83, v83
	v_rcp_f32_e32 v84, v84
	v_rcp_f32_e32 v85, v85
	v_mul_f32_e32 v94, v94, v90
	v_mul_f32_e32 v95, v95, v91
	v_mul_f32_e32 v96, v96, v92
	v_mul_f32_e32 v97, v97, v93
	v_mul_f32_e32 v86, v86, v82
	v_mul_f32_e32 v87, v87, v83
	v_mul_f32_e32 v88, v88, v84
	v_mul_f32_e32 v89, v89, v85
	v_cvt_pk_bf16_f32 v90, v94, v95
	v_cvt_pk_bf16_f32 v91, v96, v97
	v_cvt_pk_bf16_f32 v92, v86, v87
	v_cvt_pk_bf16_f32 v93, v88, v89
	global_store_dwordx4 v172, v[90:93], s[30:31]
	v_add_u32_e32 v172, 0x16000, v172
	v_mul_f32_e32 v74, v143, v74
	v_mul_f32_e32 v75, v143, v75
	v_mul_f32_e32 v76, v143, v76
	v_mul_f32_e32 v77, v143, v77
	v_mul_f32_e32 v66, v143, v66
	v_mul_f32_e32 v67, v143, v67
	v_mul_f32_e32 v68, v143, v68
	v_mul_f32_e32 v69, v143, v69
	v_exp_f32_e32 v74, v74
	v_exp_f32_e32 v75, v75
	v_exp_f32_e32 v76, v76
	v_exp_f32_e32 v77, v77
	v_exp_f32_e32 v66, v66
	v_exp_f32_e32 v67, v67
	v_exp_f32_e32 v68, v68
	v_exp_f32_e32 v69, v69
	v_fma_f32 v74, v74, v142, v142
; __device__ __forceinline__ float sigm(float x) { return __builtin_amdgcn_rcpf(1.0f + __expf(-x)); }
; __device__ __forceinline__ u32x4 pack8(f32x4 a, f32x4 b) { u32x4 w; w.x = cvt_pk_bf16(a[0], a[1]); w.y = cvt_pk_bf16(a[2], a[3]); w.z = cvt_pk_bf16(b[0], b[1]); w.w = cvt_pk_bf16(b[2], b[3]); return w; }
;     __device__ __forceinline__ void operator()(const f32x4 (&acc)[2][2][4][2], const Unit& u, int wr, int wc, int fr_, int fq_) const {
;     ...
;         for (int ai = 0; ai < 2; ++ai)
; #pragma unroll
;             for (int m = 0; m < 4; ++m) {
;                 const int row = u.pm * 256 + ai * 128 + wr * 64 + m * 16 + fr;
;                 const float rstd = rs8[ai][m];
;                 f32x4 o[2];
; #pragma unroll
;                 for (int n = 0; n < 2; ++n) { const f32x4 g = acc[ai][0][m][n] * rstd, up = acc[ai][1][m][n] * rstd;
; #pragma unroll
;                     for (int i = 0; i < 4; ++i) o[n][i] = g[i] * sigm(g[i]) * up[i]; }
;                 *(u32x4*)(ACT + (size_t)row * DFF + 128 * u.pn + 32 * wc + 8 * fq) = pack8(o[0], o[1]);
	v_fma_f32 v75, v75, v142, v142
	v_fma_f32 v76, v76, v142, v142
	v_fma_f32 v77, v77, v142, v142
	v_fma_f32 v66, v66, v142, v142
	v_fma_f32 v67, v67, v142, v142
	v_fma_f32 v68, v68, v142, v142
	v_fma_f32 v69, v69, v142, v142
	v_rcp_f32_e32 v74, v74
	v_rcp_f32_e32 v75, v75
	v_rcp_f32_e32 v76, v76
	v_rcp_f32_e32 v77, v77
	v_rcp_f32_e32 v66, v66
	v_rcp_f32_e32 v67, v67
	v_rcp_f32_e32 v68, v68
	v_rcp_f32_e32 v69, v69
	v_mul_f32_e32 v78, v78, v74
	v_mul_f32_e32 v79, v79, v75
	v_mul_f32_e32 v80, v80, v76
	v_mul_f32_e32 v81, v81, v77
	v_mul_f32_e32 v70, v70, v66
	v_mul_f32_e32 v71, v71, v67
	v_mul_f32_e32 v72, v72, v68
	v_mul_f32_e32 v73, v73, v69
	v_cvt_pk_bf16_f32 v74, v78, v79
	v_cvt_pk_bf16_f32 v75, v80, v81
	v_cvt_pk_bf16_f32 v76, v70, v71
	v_cvt_pk_bf16_f32 v77, v72, v73
	global_store_dwordx4 v172, v[74:77], s[30:31]
	v_add_u32_e32 v172, 0x6e000, v172
	v_mul_f32_e32 v58, v147, v58
	v_mul_f32_e32 v59, v147, v59
	v_mul_f32_e32 v60, v147, v60
	v_mul_f32_e32 v61, v147, v61
	v_mul_f32_e32 v50, v147, v50
	v_mul_f32_e32 v51, v147, v51
	v_mul_f32_e32 v52, v147, v52
	v_mul_f32_e32 v53, v147, v53
	v_exp_f32_e32 v58, v58
	v_exp_f32_e32 v59, v59
	v_exp_f32_e32 v60, v60
	v_exp_f32_e32 v61, v61
	v_exp_f32_e32 v50, v50
	v_exp_f32_e32 v51, v51
	v_exp_f32_e32 v52, v52
	v_exp_f32_e32 v53, v53
	v_fma_f32 v58, v58, v146, v146
	v_fma_f32 v59, v59, v146, v146
	v_fma_f32 v60, v60, v146, v146
	v_fma_f32 v61, v61, v146, v146
	v_fma_f32 v50, v50, v146, v146
	v_fma_f32 v51, v51, v146, v146
	v_fma_f32 v52, v52, v146, v146
	v_fma_f32 v53, v53, v146, v146
	v_rcp_f32_e32 v58, v58
	v_rcp_f32_e32 v59, v59
	v_rcp_f32_e32 v60, v60
	v_rcp_f32_e32 v61, v61
	v_rcp_f32_e32 v50, v50
	v_rcp_f32_e32 v51, v51
	v_rcp_f32_e32 v52, v52
	v_rcp_f32_e32 v53, v53
	v_mul_f32_e32 v62, v62, v58
	v_mul_f32_e32 v63, v63, v59
	v_mul_f32_e32 v64, v64, v60
	v_mul_f32_e32 v65, v65, v61
	v_mul_f32_e32 v54, v54, v50
	v_mul_f32_e32 v55, v55, v51
	v_mul_f32_e32 v56, v56, v52
	v_mul_f32_e32 v57, v57, v53
	v_cvt_pk_bf16_f32 v58, v62, v63
	v_cvt_pk_bf16_f32 v59, v64, v65
	v_cvt_pk_bf16_f32 v60, v54, v55
	v_cvt_pk_bf16_f32 v61, v56, v57
	global_store_dwordx4 v172, v[58:61], s[30:31]
	v_add_u32_e32 v172, 0x16000, v172
	v_mul_f32_e32 v42, v151, v42
	v_mul_f32_e32 v43, v151, v43
	v_mul_f32_e32 v44, v151, v44
	v_mul_f32_e32 v45, v151, v45
	v_mul_f32_e32 v34, v151, v34
	v_mul_f32_e32 v35, v151, v35
	v_mul_f32_e32 v36, v151, v36
	v_mul_f32_e32 v37, v151, v37
	v_exp_f32_e32 v42, v42
	v_exp_f32_e32 v43, v43
	v_exp_f32_e32 v44, v44
	v_exp_f32_e32 v45, v45
	v_exp_f32_e32 v34, v34
	v_exp_f32_e32 v35, v35
	v_exp_f32_e32 v36, v36
	v_exp_f32_e32 v37, v37
	v_fma_f32 v42, v42, v150, v150
	v_fma_f32 v43, v43, v150, v150
	v_fma_f32 v44, v44, v150, v150
	v_fma_f32 v45, v45, v150, v150
	v_fma_f32 v34, v34, v150, v150
	v_fma_f32 v35, v35, v150, v150
	v_fma_f32 v36, v36, v150, v150
	v_fma_f32 v37, v37, v150, v150
	v_rcp_f32_e32 v42, v42
	v_rcp_f32_e32 v43, v43
	v_rcp_f32_e32 v44, v44
	v_rcp_f32_e32 v45, v45
	v_rcp_f32_e32 v34, v34
	v_rcp_f32_e32 v35, v35
	v_rcp_f32_e32 v36, v36
	v_rcp_f32_e32 v37, v37
	v_mul_f32_e32 v46, v46, v42
	v_mul_f32_e32 v47, v47, v43
	v_mul_f32_e32 v48, v48, v44
	v_mul_f32_e32 v49, v49, v45
	v_mul_f32_e32 v38, v38, v34
	v_mul_f32_e32 v39, v39, v35
	v_mul_f32_e32 v40, v40, v36
	v_mul_f32_e32 v41, v41, v37
	v_cvt_pk_bf16_f32 v42, v46, v47
	v_cvt_pk_bf16_f32 v43, v48, v49
	v_cvt_pk_bf16_f32 v44, v38, v39
	v_cvt_pk_bf16_f32 v45, v40, v41
	global_store_dwordx4 v172, v[42:45], s[30:31]
	v_add_u32_e32 v172, 0x16000, v172
	v_mul_f32_e32 v26, v155, v26
	v_mul_f32_e32 v27, v155, v27
	v_mul_f32_e32 v28, v155, v28
	v_mul_f32_e32 v29, v155, v29
	v_mul_f32_e32 v18, v155, v18
	v_mul_f32_e32 v19, v155, v19
	v_mul_f32_e32 v20, v155, v20
	v_mul_f32_e32 v21, v155, v21
	v_exp_f32_e32 v26, v26
	v_exp_f32_e32 v27, v27
	v_exp_f32_e32 v28, v28
	v_exp_f32_e32 v29, v29
	v_exp_f32_e32 v18, v18
	v_exp_f32_e32 v19, v19
	v_exp_f32_e32 v20, v20
	v_exp_f32_e32 v21, v21
	v_fma_f32 v26, v26, v154, v154
	v_fma_f32 v27, v27, v154, v154
	v_fma_f32 v28, v28, v154, v154
	v_fma_f32 v29, v29, v154, v154
	v_fma_f32 v18, v18, v154, v154
	v_fma_f32 v19, v19, v154, v154
	v_fma_f32 v20, v20, v154, v154
	v_fma_f32 v21, v21, v154, v154
	v_rcp_f32_e32 v26, v26
	v_rcp_f32_e32 v27, v27
	v_rcp_f32_e32 v28, v28
	v_rcp_f32_e32 v29, v29
	v_rcp_f32_e32 v18, v18
	v_rcp_f32_e32 v19, v19
	v_rcp_f32_e32 v20, v20
	v_rcp_f32_e32 v21, v21
	v_mul_f32_e32 v30, v30, v26
	v_mul_f32_e32 v31, v31, v27
	v_mul_f32_e32 v32, v32, v28
	v_mul_f32_e32 v33, v33, v29
	v_mul_f32_e32 v22, v22, v18
	v_mul_f32_e32 v23, v23, v19
	v_mul_f32_e32 v24, v24, v20
	v_mul_f32_e32 v25, v25, v21
	v_cvt_pk_bf16_f32 v26, v30, v31
	v_cvt_pk_bf16_f32 v27, v32, v33
	v_cvt_pk_bf16_f32 v28, v22, v23
	v_cvt_pk_bf16_f32 v29, v24, v25
	global_store_dwordx4 v172, v[26:29], s[30:31]
	v_add_u32_e32 v172, 0x16000, v172
	v_mul_f32_e32 v10, v159, v10
	v_mul_f32_e32 v11, v159, v11
	v_mul_f32_e32 v12, v159, v12
	v_mul_f32_e32 v13, v159, v13
	v_mul_f32_e32 v2, v159, v2
	v_mul_f32_e32 v3, v159, v3
	v_mul_f32_e32 v4, v159, v4
	v_mul_f32_e32 v5, v159, v5
	v_exp_f32_e32 v10, v10
	v_exp_f32_e32 v11, v11
	v_exp_f32_e32 v12, v12
	v_exp_f32_e32 v13, v13
	v_exp_f32_e32 v2, v2
	v_exp_f32_e32 v3, v3
	v_exp_f32_e32 v4, v4
	v_exp_f32_e32 v5, v5
	v_fma_f32 v10, v10, v158, v158
	v_fma_f32 v11, v11, v158, v158
	v_fma_f32 v12, v12, v158, v158
	v_fma_f32 v13, v13, v158, v158
	v_fma_f32 v2, v2, v158, v158
	v_fma_f32 v3, v3, v158, v158
	v_fma_f32 v4, v4, v158, v158
	v_fma_f32 v5, v5, v158, v158
	v_rcp_f32_e32 v10, v10
	v_rcp_f32_e32 v11, v11
	v_rcp_f32_e32 v12, v12
	v_rcp_f32_e32 v13, v13
	v_rcp_f32_e32 v2, v2
	v_rcp_f32_e32 v3, v3
	v_rcp_f32_e32 v4, v4
	v_rcp_f32_e32 v5, v5
	v_mul_f32_e32 v14, v14, v10
	v_mul_f32_e32 v15, v15, v11
	v_mul_f32_e32 v16, v16, v12
	v_mul_f32_e32 v17, v17, v13
	v_mul_f32_e32 v6, v6, v2
	v_mul_f32_e32 v7, v7, v3
	v_mul_f32_e32 v8, v8, v4
	v_mul_f32_e32 v9, v9, v5
	v_cvt_pk_bf16_f32 v10, v14, v15
	v_cvt_pk_bf16_f32 v11, v16, v17
	v_cvt_pk_bf16_f32 v12, v6, v7
	v_cvt_pk_bf16_f32 v13, v8, v9
	global_store_dwordx4 v172, v[10:13], s[30:31]
	s_andn2_b64 vcc, exec, s[38:39]
	s_mov_b64 s[0:1], -1
	s_cbranch_vccnz .LBB0_43
	v_readlane_b32 s0, v255, 45
	v_readlane_b32 s1, v255, 46
	s_andn2_b64 vcc, exec, s[0:1]
	s_cbranch_vccnz .LBB0_42
	s_barrier
	s_branch .LBB0_42
